# P2 epilogue rewritten by hand with packed f32 scale / silu math and one address computation per row tile (original column layout and store pattern)
# baseline (speedup 1.0000x reference)
; __device__ __forceinline__ unsigned cvt_pk_bf16(float lo, float hi) { unsigned r; asm volatile("v_cvt_pk_bf16_f32 %0, %1, %2" : "=v"(r) : "v"(lo), "v"(hi)); return r; }
; __device__ __forceinline__ float silu_f(float x) { return x * __builtin_amdgcn_rcpf(1.0f + __expf(-x)); }
;     __device__ __forceinline__ void operator()(const f32x4 (&acc)[2][2][4][2], const Unit& u, int wr, int wc, int fr, int fq) const {
;         const int row0 = u.pm * BM + wr * 64 + fr;
; #pragma unroll
;         for (int bj = 0; bj < 2; ++bj) {
;             const int col0 = u.pn * BM + bj * HALF + wc * 32 + 8 * fq;
;             if (col0 >= 2880) continue;
;             const float sc = (col0 < 256) ? 0.125f : 1.0f;
; #pragma unroll
;             for (int ai = 0; ai < 2; ++ai)
; #pragma unroll
;                 for (int m = 0; m < 4; ++m) {
;                     f32x4 v0 = acc[ai][bj][m][0] * sc, v1 = acc[ai][bj][m][1] * sc;
;                     if (col0 >= 1024 && col0 < 2048) {
; #pragma unroll
;                         for (int e = 0; e < 4; ++e) { v0[e] = silu_f(v0[e]); v1[e] = silu_f(v1[e]); } }
;                     u32x4 w; w.x = cvt_pk_bf16(v0[0], v0[1]); w.y = cvt_pk_bf16(v0[2], v0[3]); w.z = cvt_pk_bf16(v1[0], v1[1]); w.w = cvt_pk_bf16(v1[2], v1[3]);
;                     *(u32x4*)(O + (size_t)(row0 + ai * HALF + m * 16) * 2880 + col0) = w;
;                 }
;         }
;     }
.LBB0_273:
	s_cmp_eq_u32 s86, 0
	s_cselect_b32 s0, 0x3e000000, 1.0
	v_mov_b32_e32 v158, s0
	v_mov_b32_e32 v159, s0
	s_mov_b32 s0, 0xbfb8aa3b
	v_mov_b32_e32 v164, s0
	v_mov_b32_e32 v165, s0
	s_and_b32 s0, s86, 0xfffffc
	s_cmp_eq_u32 s0, 4
	s_cselect_b64 s[90:91], -1, 0
	v_lshl_add_u32 v156, s6, 8, v1
	v_lshl_or_b32 v162, s86, 8, v151
	v_mov_b64_e32 v[160:161], s[18:19]
	v_mad_i64_i32 v[160:161], s[0:1], v156, s95, v[160:161]
	v_lshlrev_b32_e32 v162, 1, v162
	v_mov_b32_e32 v163, 0
	v_lshl_add_u64 v[160:161], v[160:161], 0, v[162:163]
	s_mov_b32 s1, 0
	v_pk_mul_f32 v[126:127], v[158:159], v[126:127]
	v_pk_mul_f32 v[128:129], v[158:159], v[128:129]
	v_pk_mul_f32 v[122:123], v[158:159], v[122:123]
	v_pk_mul_f32 v[124:125], v[158:159], v[124:125]
	v_pk_mul_f32 v[62:63], v[158:159], v[62:63]
	v_pk_mul_f32 v[64:65], v[158:159], v[64:65]
	v_pk_mul_f32 v[58:59], v[158:159], v[58:59]
	v_pk_mul_f32 v[60:61], v[158:159], v[60:61]
	s_and_b64 vcc, exec, s[90:91]
	s_cbranch_vccz .Lp2q_ns0
	v_pk_mul_f32 v[166:167], v[126:127], v[164:165]
	v_pk_mul_f32 v[168:169], v[128:129], v[164:165]
	v_pk_mul_f32 v[170:171], v[122:123], v[164:165]
	v_pk_mul_f32 v[172:173], v[124:125], v[164:165]
	v_pk_mul_f32 v[174:175], v[62:63], v[164:165]
	v_pk_mul_f32 v[176:177], v[64:65], v[164:165]
	v_pk_mul_f32 v[178:179], v[58:59], v[164:165]
	v_pk_mul_f32 v[180:181], v[60:61], v[164:165]
	v_exp_f32_e32 v166, v166
	v_exp_f32_e32 v167, v167
	v_exp_f32_e32 v168, v168
	v_exp_f32_e32 v169, v169
	v_exp_f32_e32 v170, v170
	v_exp_f32_e32 v171, v171
	v_exp_f32_e32 v172, v172
	v_exp_f32_e32 v173, v173
	v_exp_f32_e32 v174, v174
	v_exp_f32_e32 v175, v175
	v_exp_f32_e32 v176, v176
	v_exp_f32_e32 v177, v177
	v_exp_f32_e32 v178, v178
	v_exp_f32_e32 v179, v179
	v_exp_f32_e32 v180, v180
	v_exp_f32_e32 v181, v181
	v_pk_add_f32 v[166:167], v[166:167], 1.0 op_sel_hi:[1,0]
	v_pk_add_f32 v[168:169], v[168:169], 1.0 op_sel_hi:[1,0]
	v_pk_add_f32 v[170:171], v[170:171], 1.0 op_sel_hi:[1,0]
	v_pk_add_f32 v[172:173], v[172:173], 1.0 op_sel_hi:[1,0]
	v_pk_add_f32 v[174:175], v[174:175], 1.0 op_sel_hi:[1,0]
	v_pk_add_f32 v[176:177], v[176:177], 1.0 op_sel_hi:[1,0]
	v_pk_add_f32 v[178:179], v[178:179], 1.0 op_sel_hi:[1,0]
	v_pk_add_f32 v[180:181], v[180:181], 1.0 op_sel_hi:[1,0]
	v_rcp_f32_e32 v166, v166
	v_rcp_f32_e32 v167, v167
	v_rcp_f32_e32 v168, v168
	v_rcp_f32_e32 v169, v169
	v_rcp_f32_e32 v170, v170
	v_rcp_f32_e32 v171, v171
	v_rcp_f32_e32 v172, v172
	v_rcp_f32_e32 v173, v173
	v_rcp_f32_e32 v174, v174
	v_rcp_f32_e32 v175, v175
	v_rcp_f32_e32 v176, v176
	v_rcp_f32_e32 v177, v177
	v_rcp_f32_e32 v178, v178
	v_rcp_f32_e32 v179, v179
	v_rcp_f32_e32 v180, v180
	v_rcp_f32_e32 v181, v181
	v_pk_mul_f32 v[126:127], v[126:127], v[166:167]
	v_pk_mul_f32 v[128:129], v[128:129], v[168:169]
	v_pk_mul_f32 v[122:123], v[122:123], v[170:171]
	v_pk_mul_f32 v[124:125], v[124:125], v[172:173]
	v_pk_mul_f32 v[62:63], v[62:63], v[174:175]
	v_pk_mul_f32 v[64:65], v[64:65], v[176:177]
	v_pk_mul_f32 v[58:59], v[58:59], v[178:179]
	v_pk_mul_f32 v[60:61], v[60:61], v[180:181]
.Lp2q_ns0:
	v_cvt_pk_bf16_f32 v126, v126, v127
	v_cvt_pk_bf16_f32 v127, v128, v129
	v_cvt_pk_bf16_f32 v128, v122, v123
	v_cvt_pk_bf16_f32 v129, v124, v125
	v_cvt_pk_bf16_f32 v62, v62, v63
	v_cvt_pk_bf16_f32 v63, v64, v65
	v_cvt_pk_bf16_f32 v64, v58, v59
	v_cvt_pk_bf16_f32 v65, v60, v61
	global_store_dwordx4 v[160:161], v[126:129], off sc1
	global_store_dwordx4 v[160:161], v[62:65], off offset:256 sc1
	s_mov_b32 s0, 0x16800
	v_lshl_add_u64 v[160:161], v[160:161], 0, s[0:1]
	v_pk_mul_f32 v[118:119], v[158:159], v[118:119]
	v_pk_mul_f32 v[120:121], v[158:159], v[120:121]
	v_pk_mul_f32 v[114:115], v[158:159], v[114:115]
	v_pk_mul_f32 v[116:117], v[158:159], v[116:117]
	v_pk_mul_f32 v[54:55], v[158:159], v[54:55]
	v_pk_mul_f32 v[56:57], v[158:159], v[56:57]
	v_pk_mul_f32 v[50:51], v[158:159], v[50:51]
	v_pk_mul_f32 v[52:53], v[158:159], v[52:53]
	s_and_b64 vcc, exec, s[90:91]
	s_cbranch_vccz .Lp2q_ns1
	v_pk_mul_f32 v[166:167], v[118:119], v[164:165]
	v_pk_mul_f32 v[168:169], v[120:121], v[164:165]
	v_pk_mul_f32 v[170:171], v[114:115], v[164:165]
	v_pk_mul_f32 v[172:173], v[116:117], v[164:165]
	v_pk_mul_f32 v[174:175], v[54:55], v[164:165]
	v_pk_mul_f32 v[176:177], v[56:57], v[164:165]
	v_pk_mul_f32 v[178:179], v[50:51], v[164:165]
	v_pk_mul_f32 v[180:181], v[52:53], v[164:165]
	v_exp_f32_e32 v166, v166
	v_exp_f32_e32 v167, v167
	v_exp_f32_e32 v168, v168
	v_exp_f32_e32 v169, v169
	v_exp_f32_e32 v170, v170
	v_exp_f32_e32 v171, v171
	v_exp_f32_e32 v172, v172
	v_exp_f32_e32 v173, v173
	v_exp_f32_e32 v174, v174
	v_exp_f32_e32 v175, v175
	v_exp_f32_e32 v176, v176
	v_exp_f32_e32 v177, v177
	v_exp_f32_e32 v178, v178
	v_exp_f32_e32 v179, v179
	v_exp_f32_e32 v180, v180
	v_exp_f32_e32 v181, v181
	v_pk_add_f32 v[166:167], v[166:167], 1.0 op_sel_hi:[1,0]
	v_pk_add_f32 v[168:169], v[168:169], 1.0 op_sel_hi:[1,0]
	v_pk_add_f32 v[170:171], v[170:171], 1.0 op_sel_hi:[1,0]
	v_pk_add_f32 v[172:173], v[172:173], 1.0 op_sel_hi:[1,0]
	v_pk_add_f32 v[174:175], v[174:175], 1.0 op_sel_hi:[1,0]
	v_pk_add_f32 v[176:177], v[176:177], 1.0 op_sel_hi:[1,0]
	v_pk_add_f32 v[178:179], v[178:179], 1.0 op_sel_hi:[1,0]
	v_pk_add_f32 v[180:181], v[180:181], 1.0 op_sel_hi:[1,0]
	v_rcp_f32_e32 v166, v166
	v_rcp_f32_e32 v167, v167
	v_rcp_f32_e32 v168, v168
	v_rcp_f32_e32 v169, v169
	v_rcp_f32_e32 v170, v170
	v_rcp_f32_e32 v171, v171
	v_rcp_f32_e32 v172, v172
	v_rcp_f32_e32 v173, v173
	v_rcp_f32_e32 v174, v174
	v_rcp_f32_e32 v175, v175
	v_rcp_f32_e32 v176, v176
	v_rcp_f32_e32 v177, v177
	v_rcp_f32_e32 v178, v178
	v_rcp_f32_e32 v179, v179
	v_rcp_f32_e32 v180, v180
	v_rcp_f32_e32 v181, v181
	v_pk_mul_f32 v[118:119], v[118:119], v[166:167]
	v_pk_mul_f32 v[120:121], v[120:121], v[168:169]
	v_pk_mul_f32 v[114:115], v[114:115], v[170:171]
	v_pk_mul_f32 v[116:117], v[116:117], v[172:173]
	v_pk_mul_f32 v[54:55], v[54:55], v[174:175]
	v_pk_mul_f32 v[56:57], v[56:57], v[176:177]
	v_pk_mul_f32 v[50:51], v[50:51], v[178:179]
	v_pk_mul_f32 v[52:53], v[52:53], v[180:181]
; __device__ __forceinline__ unsigned cvt_pk_bf16(float lo, float hi) { unsigned r; asm volatile("v_cvt_pk_bf16_f32 %0, %1, %2" : "=v"(r) : "v"(lo), "v"(hi)); return r; }
; __device__ __forceinline__ float silu_f(float x) { return x * __builtin_amdgcn_rcpf(1.0f + __expf(-x)); }
;     __device__ __forceinline__ void operator()(const f32x4 (&acc)[2][2][4][2], const Unit& u, int wr, int wc, int fr, int fq) const {
;         const int row0 = u.pm * BM + wr * 64 + fr;
; #pragma unroll
;         for (int bj = 0; bj < 2; ++bj) {
;             const int col0 = u.pn * BM + bj * HALF + wc * 32 + 8 * fq;
;             if (col0 >= 2880) continue;
;             const float sc = (col0 < 256) ? 0.125f : 1.0f;
; #pragma unroll
;             for (int ai = 0; ai < 2; ++ai)
; #pragma unroll
;                 for (int m = 0; m < 4; ++m) {
;                     f32x4 v0 = acc[ai][bj][m][0] * sc, v1 = acc[ai][bj][m][1] * sc;
;                     if (col0 >= 1024 && col0 < 2048) {
; #pragma unroll
;                         for (int e = 0; e < 4; ++e) { v0[e] = silu_f(v0[e]); v1[e] = silu_f(v1[e]); } }
;                     u32x4 w; w.x = cvt_pk_bf16(v0[0], v0[1]); w.y = cvt_pk_bf16(v0[2], v0[3]); w.z = cvt_pk_bf16(v1[0], v1[1]); w.w = cvt_pk_bf16(v1[2], v1[3]);
;                     *(u32x4*)(O + (size_t)(row0 + ai * HALF + m * 16) * 2880 + col0) = w;
;                 }
;         }
;     }
.Lp2q_ns1:
	v_cvt_pk_bf16_f32 v118, v118, v119
	v_cvt_pk_bf16_f32 v119, v120, v121
	v_cvt_pk_bf16_f32 v120, v114, v115
	v_cvt_pk_bf16_f32 v121, v116, v117
	v_cvt_pk_bf16_f32 v54, v54, v55
	v_cvt_pk_bf16_f32 v55, v56, v57
	v_cvt_pk_bf16_f32 v56, v50, v51
	v_cvt_pk_bf16_f32 v57, v52, v53
	global_store_dwordx4 v[160:161], v[118:121], off sc1
	global_store_dwordx4 v[160:161], v[54:57], off offset:256 sc1
	s_mov_b32 s0, 0x16800
	v_lshl_add_u64 v[160:161], v[160:161], 0, s[0:1]
	v_pk_mul_f32 v[110:111], v[158:159], v[110:111]
	v_pk_mul_f32 v[112:113], v[158:159], v[112:113]
	v_pk_mul_f32 v[106:107], v[158:159], v[106:107]
	v_pk_mul_f32 v[108:109], v[158:159], v[108:109]
	v_pk_mul_f32 v[46:47], v[158:159], v[46:47]
	v_pk_mul_f32 v[48:49], v[158:159], v[48:49]
	v_pk_mul_f32 v[42:43], v[158:159], v[42:43]
	v_pk_mul_f32 v[44:45], v[158:159], v[44:45]
	s_and_b64 vcc, exec, s[90:91]
	s_cbranch_vccz .Lp2q_ns2
	v_pk_mul_f32 v[166:167], v[110:111], v[164:165]
	v_pk_mul_f32 v[168:169], v[112:113], v[164:165]
	v_pk_mul_f32 v[170:171], v[106:107], v[164:165]
	v_pk_mul_f32 v[172:173], v[108:109], v[164:165]
	v_pk_mul_f32 v[174:175], v[46:47], v[164:165]
	v_pk_mul_f32 v[176:177], v[48:49], v[164:165]
	v_pk_mul_f32 v[178:179], v[42:43], v[164:165]
	v_pk_mul_f32 v[180:181], v[44:45], v[164:165]
	v_exp_f32_e32 v166, v166
	v_exp_f32_e32 v167, v167
	v_exp_f32_e32 v168, v168
	v_exp_f32_e32 v169, v169
	v_exp_f32_e32 v170, v170
	v_exp_f32_e32 v171, v171
	v_exp_f32_e32 v172, v172
	v_exp_f32_e32 v173, v173
	v_exp_f32_e32 v174, v174
	v_exp_f32_e32 v175, v175
	v_exp_f32_e32 v176, v176
	v_exp_f32_e32 v177, v177
	v_exp_f32_e32 v178, v178
	v_exp_f32_e32 v179, v179
	v_exp_f32_e32 v180, v180
	v_exp_f32_e32 v181, v181
	v_pk_add_f32 v[166:167], v[166:167], 1.0 op_sel_hi:[1,0]
	v_pk_add_f32 v[168:169], v[168:169], 1.0 op_sel_hi:[1,0]
	v_pk_add_f32 v[170:171], v[170:171], 1.0 op_sel_hi:[1,0]
	v_pk_add_f32 v[172:173], v[172:173], 1.0 op_sel_hi:[1,0]
	v_pk_add_f32 v[174:175], v[174:175], 1.0 op_sel_hi:[1,0]
	v_pk_add_f32 v[176:177], v[176:177], 1.0 op_sel_hi:[1,0]
	v_pk_add_f32 v[178:179], v[178:179], 1.0 op_sel_hi:[1,0]
	v_pk_add_f32 v[180:181], v[180:181], 1.0 op_sel_hi:[1,0]
	v_rcp_f32_e32 v166, v166
	v_rcp_f32_e32 v167, v167
	v_rcp_f32_e32 v168, v168
	v_rcp_f32_e32 v169, v169
	v_rcp_f32_e32 v170, v170
	v_rcp_f32_e32 v171, v171
	v_rcp_f32_e32 v172, v172
	v_rcp_f32_e32 v173, v173
	v_rcp_f32_e32 v174, v174
	v_rcp_f32_e32 v175, v175
	v_rcp_f32_e32 v176, v176
	v_rcp_f32_e32 v177, v177
	v_rcp_f32_e32 v178, v178
	v_rcp_f32_e32 v179, v179
	v_rcp_f32_e32 v180, v180
	v_rcp_f32_e32 v181, v181
	v_pk_mul_f32 v[110:111], v[110:111], v[166:167]
	v_pk_mul_f32 v[112:113], v[112:113], v[168:169]
	v_pk_mul_f32 v[106:107], v[106:107], v[170:171]
	v_pk_mul_f32 v[108:109], v[108:109], v[172:173]
	v_pk_mul_f32 v[46:47], v[46:47], v[174:175]
	v_pk_mul_f32 v[48:49], v[48:49], v[176:177]
	v_pk_mul_f32 v[42:43], v[42:43], v[178:179]
	v_pk_mul_f32 v[44:45], v[44:45], v[180:181]
.Lp2q_ns2:
	v_cvt_pk_bf16_f32 v110, v110, v111
	v_cvt_pk_bf16_f32 v111, v112, v113
	v_cvt_pk_bf16_f32 v112, v106, v107
	v_cvt_pk_bf16_f32 v113, v108, v109
	v_cvt_pk_bf16_f32 v46, v46, v47
	v_cvt_pk_bf16_f32 v47, v48, v49
	v_cvt_pk_bf16_f32 v48, v42, v43
	v_cvt_pk_bf16_f32 v49, v44, v45
	global_store_dwordx4 v[160:161], v[110:113], off sc1
	global_store_dwordx4 v[160:161], v[46:49], off offset:256 sc1
	s_mov_b32 s0, 0x16800
	v_lshl_add_u64 v[160:161], v[160:161], 0, s[0:1]
	v_pk_mul_f32 v[102:103], v[158:159], v[102:103]
	v_pk_mul_f32 v[104:105], v[158:159], v[104:105]
	v_pk_mul_f32 v[98:99], v[158:159], v[98:99]
	v_pk_mul_f32 v[100:101], v[158:159], v[100:101]
	v_pk_mul_f32 v[38:39], v[158:159], v[38:39]
	v_pk_mul_f32 v[40:41], v[158:159], v[40:41]
	v_pk_mul_f32 v[34:35], v[158:159], v[34:35]
	v_pk_mul_f32 v[36:37], v[158:159], v[36:37]
	s_and_b64 vcc, exec, s[90:91]
	s_cbranch_vccz .Lp2q_ns3
	v_pk_mul_f32 v[166:167], v[102:103], v[164:165]
	v_pk_mul_f32 v[168:169], v[104:105], v[164:165]
	v_pk_mul_f32 v[170:171], v[98:99], v[164:165]
	v_pk_mul_f32 v[172:173], v[100:101], v[164:165]
	v_pk_mul_f32 v[174:175], v[38:39], v[164:165]
	v_pk_mul_f32 v[176:177], v[40:41], v[164:165]
	v_pk_mul_f32 v[178:179], v[34:35], v[164:165]
	v_pk_mul_f32 v[180:181], v[36:37], v[164:165]
	v_exp_f32_e32 v166, v166
	v_exp_f32_e32 v167, v167
	v_exp_f32_e32 v168, v168
	v_exp_f32_e32 v169, v169
	v_exp_f32_e32 v170, v170
	v_exp_f32_e32 v171, v171
	v_exp_f32_e32 v172, v172
	v_exp_f32_e32 v173, v173
	v_exp_f32_e32 v174, v174
	v_exp_f32_e32 v175, v175
	v_exp_f32_e32 v176, v176
	v_exp_f32_e32 v177, v177
	v_exp_f32_e32 v178, v178
	v_exp_f32_e32 v179, v179
	v_exp_f32_e32 v180, v180
	v_exp_f32_e32 v181, v181
	v_pk_add_f32 v[166:167], v[166:167], 1.0 op_sel_hi:[1,0]
	v_pk_add_f32 v[168:169], v[168:169], 1.0 op_sel_hi:[1,0]
	v_pk_add_f32 v[170:171], v[170:171], 1.0 op_sel_hi:[1,0]
	v_pk_add_f32 v[172:173], v[172:173], 1.0 op_sel_hi:[1,0]
	v_pk_add_f32 v[174:175], v[174:175], 1.0 op_sel_hi:[1,0]
	v_pk_add_f32 v[176:177], v[176:177], 1.0 op_sel_hi:[1,0]
	v_pk_add_f32 v[178:179], v[178:179], 1.0 op_sel_hi:[1,0]
	v_pk_add_f32 v[180:181], v[180:181], 1.0 op_sel_hi:[1,0]
	v_rcp_f32_e32 v166, v166
	v_rcp_f32_e32 v167, v167
	v_rcp_f32_e32 v168, v168
	v_rcp_f32_e32 v169, v169
	v_rcp_f32_e32 v170, v170
	v_rcp_f32_e32 v171, v171
	v_rcp_f32_e32 v172, v172
	v_rcp_f32_e32 v173, v173
	v_rcp_f32_e32 v174, v174
	v_rcp_f32_e32 v175, v175
	v_rcp_f32_e32 v176, v176
	v_rcp_f32_e32 v177, v177
	v_rcp_f32_e32 v178, v178
	v_rcp_f32_e32 v179, v179
	v_rcp_f32_e32 v180, v180
	v_rcp_f32_e32 v181, v181
	v_pk_mul_f32 v[102:103], v[102:103], v[166:167]
	v_pk_mul_f32 v[104:105], v[104:105], v[168:169]
	v_pk_mul_f32 v[98:99], v[98:99], v[170:171]
	v_pk_mul_f32 v[100:101], v[100:101], v[172:173]
	v_pk_mul_f32 v[38:39], v[38:39], v[174:175]
	v_pk_mul_f32 v[40:41], v[40:41], v[176:177]
	v_pk_mul_f32 v[34:35], v[34:35], v[178:179]
	v_pk_mul_f32 v[36:37], v[36:37], v[180:181]
; __device__ __forceinline__ unsigned cvt_pk_bf16(float lo, float hi) { unsigned r; asm volatile("v_cvt_pk_bf16_f32 %0, %1, %2" : "=v"(r) : "v"(lo), "v"(hi)); return r; }
; __device__ __forceinline__ float silu_f(float x) { return x * __builtin_amdgcn_rcpf(1.0f + __expf(-x)); }
;     __device__ __forceinline__ void operator()(const f32x4 (&acc)[2][2][4][2], const Unit& u, int wr, int wc, int fr, int fq) const {
;         const int row0 = u.pm * BM + wr * 64 + fr;
; #pragma unroll
;         for (int bj = 0; bj < 2; ++bj) {
;             const int col0 = u.pn * BM + bj * HALF + wc * 32 + 8 * fq;
;             if (col0 >= 2880) continue;
;             const float sc = (col0 < 256) ? 0.125f : 1.0f;
; #pragma unroll
;             for (int ai = 0; ai < 2; ++ai)
; #pragma unroll
;                 for (int m = 0; m < 4; ++m) {
;                     f32x4 v0 = acc[ai][bj][m][0] * sc, v1 = acc[ai][bj][m][1] * sc;
;                     if (col0 >= 1024 && col0 < 2048) {
; #pragma unroll
;                         for (int e = 0; e < 4; ++e) { v0[e] = silu_f(v0[e]); v1[e] = silu_f(v1[e]); } }
;                     u32x4 w; w.x = cvt_pk_bf16(v0[0], v0[1]); w.y = cvt_pk_bf16(v0[2], v0[3]); w.z = cvt_pk_bf16(v1[0], v1[1]); w.w = cvt_pk_bf16(v1[2], v1[3]);
;                     *(u32x4*)(O + (size_t)(row0 + ai * HALF + m * 16) * 2880 + col0) = w;
;                 }
;         }
;     }
.Lp2q_ns3:
	v_cvt_pk_bf16_f32 v102, v102, v103
	v_cvt_pk_bf16_f32 v103, v104, v105
	v_cvt_pk_bf16_f32 v104, v98, v99
	v_cvt_pk_bf16_f32 v105, v100, v101
	v_cvt_pk_bf16_f32 v38, v38, v39
	v_cvt_pk_bf16_f32 v39, v40, v41
	v_cvt_pk_bf16_f32 v40, v34, v35
	v_cvt_pk_bf16_f32 v41, v36, v37
	global_store_dwordx4 v[160:161], v[102:105], off sc1
	global_store_dwordx4 v[160:161], v[38:41], off offset:256 sc1
	s_mov_b32 s0, 0x70800
	v_lshl_add_u64 v[160:161], v[160:161], 0, s[0:1]
	v_pk_mul_f32 v[94:95], v[158:159], v[94:95]
	v_pk_mul_f32 v[96:97], v[158:159], v[96:97]
	v_pk_mul_f32 v[90:91], v[158:159], v[90:91]
	v_pk_mul_f32 v[92:93], v[158:159], v[92:93]
	v_pk_mul_f32 v[30:31], v[158:159], v[30:31]
	v_pk_mul_f32 v[32:33], v[158:159], v[32:33]
	v_pk_mul_f32 v[26:27], v[158:159], v[26:27]
	v_pk_mul_f32 v[28:29], v[158:159], v[28:29]
	s_and_b64 vcc, exec, s[90:91]
	s_cbranch_vccz .Lp2q_ns4
	v_pk_mul_f32 v[166:167], v[94:95], v[164:165]
	v_pk_mul_f32 v[168:169], v[96:97], v[164:165]
	v_pk_mul_f32 v[170:171], v[90:91], v[164:165]
	v_pk_mul_f32 v[172:173], v[92:93], v[164:165]
	v_pk_mul_f32 v[174:175], v[30:31], v[164:165]
	v_pk_mul_f32 v[176:177], v[32:33], v[164:165]
	v_pk_mul_f32 v[178:179], v[26:27], v[164:165]
	v_pk_mul_f32 v[180:181], v[28:29], v[164:165]
	v_exp_f32_e32 v166, v166
	v_exp_f32_e32 v167, v167
	v_exp_f32_e32 v168, v168
	v_exp_f32_e32 v169, v169
	v_exp_f32_e32 v170, v170
	v_exp_f32_e32 v171, v171
	v_exp_f32_e32 v172, v172
	v_exp_f32_e32 v173, v173
	v_exp_f32_e32 v174, v174
	v_exp_f32_e32 v175, v175
	v_exp_f32_e32 v176, v176
	v_exp_f32_e32 v177, v177
	v_exp_f32_e32 v178, v178
	v_exp_f32_e32 v179, v179
	v_exp_f32_e32 v180, v180
	v_exp_f32_e32 v181, v181
	v_pk_add_f32 v[166:167], v[166:167], 1.0 op_sel_hi:[1,0]
	v_pk_add_f32 v[168:169], v[168:169], 1.0 op_sel_hi:[1,0]
	v_pk_add_f32 v[170:171], v[170:171], 1.0 op_sel_hi:[1,0]
	v_pk_add_f32 v[172:173], v[172:173], 1.0 op_sel_hi:[1,0]
	v_pk_add_f32 v[174:175], v[174:175], 1.0 op_sel_hi:[1,0]
	v_pk_add_f32 v[176:177], v[176:177], 1.0 op_sel_hi:[1,0]
	v_pk_add_f32 v[178:179], v[178:179], 1.0 op_sel_hi:[1,0]
	v_pk_add_f32 v[180:181], v[180:181], 1.0 op_sel_hi:[1,0]
	v_rcp_f32_e32 v166, v166
	v_rcp_f32_e32 v167, v167
	v_rcp_f32_e32 v168, v168
	v_rcp_f32_e32 v169, v169
	v_rcp_f32_e32 v170, v170
	v_rcp_f32_e32 v171, v171
	v_rcp_f32_e32 v172, v172
	v_rcp_f32_e32 v173, v173
	v_rcp_f32_e32 v174, v174
	v_rcp_f32_e32 v175, v175
	v_rcp_f32_e32 v176, v176
	v_rcp_f32_e32 v177, v177
	v_rcp_f32_e32 v178, v178
	v_rcp_f32_e32 v179, v179
	v_rcp_f32_e32 v180, v180
	v_rcp_f32_e32 v181, v181
	v_pk_mul_f32 v[94:95], v[94:95], v[166:167]
	v_pk_mul_f32 v[96:97], v[96:97], v[168:169]
	v_pk_mul_f32 v[90:91], v[90:91], v[170:171]
	v_pk_mul_f32 v[92:93], v[92:93], v[172:173]
	v_pk_mul_f32 v[30:31], v[30:31], v[174:175]
	v_pk_mul_f32 v[32:33], v[32:33], v[176:177]
	v_pk_mul_f32 v[26:27], v[26:27], v[178:179]
	v_pk_mul_f32 v[28:29], v[28:29], v[180:181]
.Lp2q_ns4:
	v_cvt_pk_bf16_f32 v94, v94, v95
	v_cvt_pk_bf16_f32 v95, v96, v97
	v_cvt_pk_bf16_f32 v96, v90, v91
	v_cvt_pk_bf16_f32 v97, v92, v93
	v_cvt_pk_bf16_f32 v30, v30, v31
	v_cvt_pk_bf16_f32 v31, v32, v33
	v_cvt_pk_bf16_f32 v32, v26, v27
	v_cvt_pk_bf16_f32 v33, v28, v29
	global_store_dwordx4 v[160:161], v[94:97], off sc1
	global_store_dwordx4 v[160:161], v[30:33], off offset:256 sc1
	s_mov_b32 s0, 0x16800
	v_lshl_add_u64 v[160:161], v[160:161], 0, s[0:1]
	v_pk_mul_f32 v[86:87], v[158:159], v[86:87]
	v_pk_mul_f32 v[88:89], v[158:159], v[88:89]
	v_pk_mul_f32 v[82:83], v[158:159], v[82:83]
	v_pk_mul_f32 v[84:85], v[158:159], v[84:85]
	v_pk_mul_f32 v[22:23], v[158:159], v[22:23]
	v_pk_mul_f32 v[24:25], v[158:159], v[24:25]
	v_pk_mul_f32 v[18:19], v[158:159], v[18:19]
	v_pk_mul_f32 v[20:21], v[158:159], v[20:21]
	s_and_b64 vcc, exec, s[90:91]
	s_cbranch_vccz .Lp2q_ns5
	v_pk_mul_f32 v[166:167], v[86:87], v[164:165]
	v_pk_mul_f32 v[168:169], v[88:89], v[164:165]
	v_pk_mul_f32 v[170:171], v[82:83], v[164:165]
	v_pk_mul_f32 v[172:173], v[84:85], v[164:165]
	v_pk_mul_f32 v[174:175], v[22:23], v[164:165]
	v_pk_mul_f32 v[176:177], v[24:25], v[164:165]
	v_pk_mul_f32 v[178:179], v[18:19], v[164:165]
	v_pk_mul_f32 v[180:181], v[20:21], v[164:165]
	v_exp_f32_e32 v166, v166
	v_exp_f32_e32 v167, v167
	v_exp_f32_e32 v168, v168
	v_exp_f32_e32 v169, v169
	v_exp_f32_e32 v170, v170
	v_exp_f32_e32 v171, v171
	v_exp_f32_e32 v172, v172
	v_exp_f32_e32 v173, v173
	v_exp_f32_e32 v174, v174
	v_exp_f32_e32 v175, v175
	v_exp_f32_e32 v176, v176
	v_exp_f32_e32 v177, v177
	v_exp_f32_e32 v178, v178
	v_exp_f32_e32 v179, v179
	v_exp_f32_e32 v180, v180
	v_exp_f32_e32 v181, v181
	v_pk_add_f32 v[166:167], v[166:167], 1.0 op_sel_hi:[1,0]
	v_pk_add_f32 v[168:169], v[168:169], 1.0 op_sel_hi:[1,0]
	v_pk_add_f32 v[170:171], v[170:171], 1.0 op_sel_hi:[1,0]
	v_pk_add_f32 v[172:173], v[172:173], 1.0 op_sel_hi:[1,0]
	v_pk_add_f32 v[174:175], v[174:175], 1.0 op_sel_hi:[1,0]
	v_pk_add_f32 v[176:177], v[176:177], 1.0 op_sel_hi:[1,0]
	v_pk_add_f32 v[178:179], v[178:179], 1.0 op_sel_hi:[1,0]
	v_pk_add_f32 v[180:181], v[180:181], 1.0 op_sel_hi:[1,0]
	v_rcp_f32_e32 v166, v166
	v_rcp_f32_e32 v167, v167
	v_rcp_f32_e32 v168, v168
	v_rcp_f32_e32 v169, v169
	v_rcp_f32_e32 v170, v170
	v_rcp_f32_e32 v171, v171
	v_rcp_f32_e32 v172, v172
	v_rcp_f32_e32 v173, v173
	v_rcp_f32_e32 v174, v174
	v_rcp_f32_e32 v175, v175
	v_rcp_f32_e32 v176, v176
	v_rcp_f32_e32 v177, v177
	v_rcp_f32_e32 v178, v178
	v_rcp_f32_e32 v179, v179
	v_rcp_f32_e32 v180, v180
	v_rcp_f32_e32 v181, v181
	v_pk_mul_f32 v[86:87], v[86:87], v[166:167]
	v_pk_mul_f32 v[88:89], v[88:89], v[168:169]
	v_pk_mul_f32 v[82:83], v[82:83], v[170:171]
	v_pk_mul_f32 v[84:85], v[84:85], v[172:173]
	v_pk_mul_f32 v[22:23], v[22:23], v[174:175]
	v_pk_mul_f32 v[24:25], v[24:25], v[176:177]
	v_pk_mul_f32 v[18:19], v[18:19], v[178:179]
	v_pk_mul_f32 v[20:21], v[20:21], v[180:181]
; __device__ __forceinline__ unsigned cvt_pk_bf16(float lo, float hi) { unsigned r; asm volatile("v_cvt_pk_bf16_f32 %0, %1, %2" : "=v"(r) : "v"(lo), "v"(hi)); return r; }
; __device__ __forceinline__ float silu_f(float x) { return x * __builtin_amdgcn_rcpf(1.0f + __expf(-x)); }
;     __device__ __forceinline__ void operator()(const f32x4 (&acc)[2][2][4][2], const Unit& u, int wr, int wc, int fr, int fq) const {
;         const int row0 = u.pm * BM + wr * 64 + fr;
; #pragma unroll
;         for (int bj = 0; bj < 2; ++bj) {
;             const int col0 = u.pn * BM + bj * HALF + wc * 32 + 8 * fq;
;             if (col0 >= 2880) continue;
;             const float sc = (col0 < 256) ? 0.125f : 1.0f;
; #pragma unroll
;             for (int ai = 0; ai < 2; ++ai)
; #pragma unroll
;                 for (int m = 0; m < 4; ++m) {
;                     f32x4 v0 = acc[ai][bj][m][0] * sc, v1 = acc[ai][bj][m][1] * sc;
;                     if (col0 >= 1024 && col0 < 2048) {
; #pragma unroll
;                         for (int e = 0; e < 4; ++e) { v0[e] = silu_f(v0[e]); v1[e] = silu_f(v1[e]); } }
;                     u32x4 w; w.x = cvt_pk_bf16(v0[0], v0[1]); w.y = cvt_pk_bf16(v0[2], v0[3]); w.z = cvt_pk_bf16(v1[0], v1[1]); w.w = cvt_pk_bf16(v1[2], v1[3]);
;                     *(u32x4*)(O + (size_t)(row0 + ai * HALF + m * 16) * 2880 + col0) = w;
;                 }
;         }
;     }
.Lp2q_ns5:
	v_cvt_pk_bf16_f32 v86, v86, v87
	v_cvt_pk_bf16_f32 v87, v88, v89
	v_cvt_pk_bf16_f32 v88, v82, v83
	v_cvt_pk_bf16_f32 v89, v84, v85
	v_cvt_pk_bf16_f32 v22, v22, v23
	v_cvt_pk_bf16_f32 v23, v24, v25
	v_cvt_pk_bf16_f32 v24, v18, v19
	v_cvt_pk_bf16_f32 v25, v20, v21
	global_store_dwordx4 v[160:161], v[86:89], off sc1
	global_store_dwordx4 v[160:161], v[22:25], off offset:256 sc1
	s_mov_b32 s0, 0x16800
	v_lshl_add_u64 v[160:161], v[160:161], 0, s[0:1]
	v_pk_mul_f32 v[78:79], v[158:159], v[78:79]
	v_pk_mul_f32 v[80:81], v[158:159], v[80:81]
	v_pk_mul_f32 v[74:75], v[158:159], v[74:75]
	v_pk_mul_f32 v[76:77], v[158:159], v[76:77]
	v_pk_mul_f32 v[14:15], v[158:159], v[14:15]
	v_pk_mul_f32 v[16:17], v[158:159], v[16:17]
	v_pk_mul_f32 v[10:11], v[158:159], v[10:11]
	v_pk_mul_f32 v[12:13], v[158:159], v[12:13]
	s_and_b64 vcc, exec, s[90:91]
	s_cbranch_vccz .Lp2q_ns6
	v_pk_mul_f32 v[166:167], v[78:79], v[164:165]
	v_pk_mul_f32 v[168:169], v[80:81], v[164:165]
	v_pk_mul_f32 v[170:171], v[74:75], v[164:165]
	v_pk_mul_f32 v[172:173], v[76:77], v[164:165]
	v_pk_mul_f32 v[174:175], v[14:15], v[164:165]
	v_pk_mul_f32 v[176:177], v[16:17], v[164:165]
	v_pk_mul_f32 v[178:179], v[10:11], v[164:165]
	v_pk_mul_f32 v[180:181], v[12:13], v[164:165]
	v_exp_f32_e32 v166, v166
	v_exp_f32_e32 v167, v167
	v_exp_f32_e32 v168, v168
	v_exp_f32_e32 v169, v169
	v_exp_f32_e32 v170, v170
	v_exp_f32_e32 v171, v171
	v_exp_f32_e32 v172, v172
	v_exp_f32_e32 v173, v173
	v_exp_f32_e32 v174, v174
	v_exp_f32_e32 v175, v175
	v_exp_f32_e32 v176, v176
	v_exp_f32_e32 v177, v177
	v_exp_f32_e32 v178, v178
	v_exp_f32_e32 v179, v179
	v_exp_f32_e32 v180, v180
	v_exp_f32_e32 v181, v181
	v_pk_add_f32 v[166:167], v[166:167], 1.0 op_sel_hi:[1,0]
	v_pk_add_f32 v[168:169], v[168:169], 1.0 op_sel_hi:[1,0]
	v_pk_add_f32 v[170:171], v[170:171], 1.0 op_sel_hi:[1,0]
	v_pk_add_f32 v[172:173], v[172:173], 1.0 op_sel_hi:[1,0]
	v_pk_add_f32 v[174:175], v[174:175], 1.0 op_sel_hi:[1,0]
	v_pk_add_f32 v[176:177], v[176:177], 1.0 op_sel_hi:[1,0]
	v_pk_add_f32 v[178:179], v[178:179], 1.0 op_sel_hi:[1,0]
	v_pk_add_f32 v[180:181], v[180:181], 1.0 op_sel_hi:[1,0]
	v_rcp_f32_e32 v166, v166
	v_rcp_f32_e32 v167, v167
	v_rcp_f32_e32 v168, v168
	v_rcp_f32_e32 v169, v169
	v_rcp_f32_e32 v170, v170
	v_rcp_f32_e32 v171, v171
	v_rcp_f32_e32 v172, v172
	v_rcp_f32_e32 v173, v173
	v_rcp_f32_e32 v174, v174
	v_rcp_f32_e32 v175, v175
	v_rcp_f32_e32 v176, v176
	v_rcp_f32_e32 v177, v177
	v_rcp_f32_e32 v178, v178
	v_rcp_f32_e32 v179, v179
	v_rcp_f32_e32 v180, v180
	v_rcp_f32_e32 v181, v181
	v_pk_mul_f32 v[78:79], v[78:79], v[166:167]
	v_pk_mul_f32 v[80:81], v[80:81], v[168:169]
	v_pk_mul_f32 v[74:75], v[74:75], v[170:171]
	v_pk_mul_f32 v[76:77], v[76:77], v[172:173]
	v_pk_mul_f32 v[14:15], v[14:15], v[174:175]
	v_pk_mul_f32 v[16:17], v[16:17], v[176:177]
	v_pk_mul_f32 v[10:11], v[10:11], v[178:179]
	v_pk_mul_f32 v[12:13], v[12:13], v[180:181]
.Lp2q_ns6:
	v_cvt_pk_bf16_f32 v78, v78, v79
	v_cvt_pk_bf16_f32 v79, v80, v81
	v_cvt_pk_bf16_f32 v80, v74, v75
	v_cvt_pk_bf16_f32 v81, v76, v77
	v_cvt_pk_bf16_f32 v14, v14, v15
	v_cvt_pk_bf16_f32 v15, v16, v17
	v_cvt_pk_bf16_f32 v16, v10, v11
	v_cvt_pk_bf16_f32 v17, v12, v13
	global_store_dwordx4 v[160:161], v[78:81], off sc1
	global_store_dwordx4 v[160:161], v[14:17], off offset:256 sc1
	s_mov_b32 s0, 0x16800
	v_lshl_add_u64 v[160:161], v[160:161], 0, s[0:1]
	v_pk_mul_f32 v[70:71], v[158:159], v[70:71]
	v_pk_mul_f32 v[72:73], v[158:159], v[72:73]
	v_pk_mul_f32 v[66:67], v[158:159], v[66:67]
	v_pk_mul_f32 v[68:69], v[158:159], v[68:69]
	v_pk_mul_f32 v[6:7], v[158:159], v[6:7]
	v_pk_mul_f32 v[8:9], v[158:159], v[8:9]
	v_pk_mul_f32 v[2:3], v[158:159], v[2:3]
	v_pk_mul_f32 v[4:5], v[158:159], v[4:5]
	s_and_b64 vcc, exec, s[90:91]
	s_cbranch_vccz .Lp2q_ns7
	v_pk_mul_f32 v[166:167], v[70:71], v[164:165]
	v_pk_mul_f32 v[168:169], v[72:73], v[164:165]
	v_pk_mul_f32 v[170:171], v[66:67], v[164:165]
	v_pk_mul_f32 v[172:173], v[68:69], v[164:165]
	v_pk_mul_f32 v[174:175], v[6:7], v[164:165]
	v_pk_mul_f32 v[176:177], v[8:9], v[164:165]
	v_pk_mul_f32 v[178:179], v[2:3], v[164:165]
	v_pk_mul_f32 v[180:181], v[4:5], v[164:165]
	v_exp_f32_e32 v166, v166
	v_exp_f32_e32 v167, v167
	v_exp_f32_e32 v168, v168
	v_exp_f32_e32 v169, v169
	v_exp_f32_e32 v170, v170
	v_exp_f32_e32 v171, v171
	v_exp_f32_e32 v172, v172
	v_exp_f32_e32 v173, v173
	v_exp_f32_e32 v174, v174
	v_exp_f32_e32 v175, v175
	v_exp_f32_e32 v176, v176
	v_exp_f32_e32 v177, v177
	v_exp_f32_e32 v178, v178
	v_exp_f32_e32 v179, v179
	v_exp_f32_e32 v180, v180
	v_exp_f32_e32 v181, v181
	v_pk_add_f32 v[166:167], v[166:167], 1.0 op_sel_hi:[1,0]
	v_pk_add_f32 v[168:169], v[168:169], 1.0 op_sel_hi:[1,0]
	v_pk_add_f32 v[170:171], v[170:171], 1.0 op_sel_hi:[1,0]
	v_pk_add_f32 v[172:173], v[172:173], 1.0 op_sel_hi:[1,0]
	v_pk_add_f32 v[174:175], v[174:175], 1.0 op_sel_hi:[1,0]
	v_pk_add_f32 v[176:177], v[176:177], 1.0 op_sel_hi:[1,0]
	v_pk_add_f32 v[178:179], v[178:179], 1.0 op_sel_hi:[1,0]
	v_pk_add_f32 v[180:181], v[180:181], 1.0 op_sel_hi:[1,0]
	v_rcp_f32_e32 v166, v166
	v_rcp_f32_e32 v167, v167
	v_rcp_f32_e32 v168, v168
	v_rcp_f32_e32 v169, v169
	v_rcp_f32_e32 v170, v170
	v_rcp_f32_e32 v171, v171
	v_rcp_f32_e32 v172, v172
	v_rcp_f32_e32 v173, v173
	v_rcp_f32_e32 v174, v174
	v_rcp_f32_e32 v175, v175
	v_rcp_f32_e32 v176, v176
	v_rcp_f32_e32 v177, v177
	v_rcp_f32_e32 v178, v178
	v_rcp_f32_e32 v179, v179
	v_rcp_f32_e32 v180, v180
	v_rcp_f32_e32 v181, v181
	v_pk_mul_f32 v[70:71], v[70:71], v[166:167]
	v_pk_mul_f32 v[72:73], v[72:73], v[168:169]
	v_pk_mul_f32 v[66:67], v[66:67], v[170:171]
	v_pk_mul_f32 v[68:69], v[68:69], v[172:173]
	v_pk_mul_f32 v[6:7], v[6:7], v[174:175]
	v_pk_mul_f32 v[8:9], v[8:9], v[176:177]
	v_pk_mul_f32 v[2:3], v[2:3], v[178:179]
	v_pk_mul_f32 v[4:5], v[4:5], v[180:181]
.Lp2q_ns7:
	v_cvt_pk_bf16_f32 v70, v70, v71
	v_cvt_pk_bf16_f32 v71, v72, v73
	v_cvt_pk_bf16_f32 v72, v66, v67
	v_cvt_pk_bf16_f32 v73, v68, v69
	v_cvt_pk_bf16_f32 v6, v6, v7
	v_cvt_pk_bf16_f32 v7, v8, v9
	v_cvt_pk_bf16_f32 v8, v2, v3
	v_cvt_pk_bf16_f32 v9, v4, v5
	global_store_dwordx4 v[160:161], v[70:73], off sc1
	global_store_dwordx4 v[160:161], v[6:9], off offset:256 sc1
	s_andn2_b64 vcc, exec, s[4:5]
	s_mov_b64 s[0:1], -1
	s_cbranch_vccnz .LBB0_262
	s_andn2_b64 vcc, exec, s[26:27]
	s_cbranch_vccnz .LBB0_261
	s_barrier
	s_branch .LBB0_261
